# glu phase: all pooling items on the 124 workgroups that have no GLU tile
# baseline (speedup 1.0000x reference)
; __device__ __forceinline__ int lane_id_v() { int l; asm volatile("v_mbcnt_lo_u32_b32 %0, -1, 0\n\tv_mbcnt_hi_u32_b32 %0, -1, %0" : "=v"(l)); return l; }
; DI void pool_phase(ArgsP a, int l, const float* XA, bf16_t* Dm, int gt  , int NT  , int lo, int hi  , bool do_sample) {
;     constexpr int NRUN = MP / 8;
;     for (int item = lo + gt; item < hi; item += NT) {
;         const int c4l = item & 31, gr = item >> 5, g = gr / NRUN, run = gr - g * NRUN; const int c4 = g * 128 + c4l * 4, row0 = run * 8;
; __global__ void __launch_bounds__(512, 2) mega(Args a_unused) {
;     ...
;                   constexpr int NI = 4 * (MP / 8) * 32; const float* XAp = (const float*)(ws + WS_XA); bf16_t* Dp = (bf16_t*)(ws + WS_DYY); const int t_ = wave_s * 64 + lane_id_v();
;                   if (G > 132) { constexpr int SPLIT = (NI / 6 * 5) & ~63;
;                       if (c >= 132) pool_phase(a, l, XAp, Dp, (c - 132) * 512 + t_, (G - 132) * 512, 0, SPLIT, true);
;                       else pool_phase(a, l, XAp, Dp, c * 512 + t_, 132 * 512, SPLIT, NI, false); }
;                   else pool_phase(a, l, XAp, Dp, c * 512 + t_, G * 512, 0, NI, true); } }
.LBB0_612:
	s_and_b64 vcc, exec, s[4:5]
	s_cbranch_vccz .LBB0_878
	s_lshl_b32 s28, s38, 9
	s_cmpk_lt_i32 s38, 0x84
	s_mov_b64 s[4:5], -1
	s_cbranch_scc0 .LBB0_742
	v_add_u32_e32 v0, s28, v114
	s_mov_b32 s4, 0
	v_cmp_gt_i32_e32 vcc, s4, v0
	s_and_saveexec_b64 s[4:5], vcc
	s_cbranch_execz .LBB0_741
	s_add_u32 s10, s24, 0x4600000
	v_readlane_b32 s6, v254, 10
	s_addc_u32 s11, s25, 0
	s_add_i32 s6, s28, s6
	v_mov_b32_e32 v1, 0xd5500
	v_add_u32_e32 v96, s6, v115
	v_lshl_add_u32 v115, v0, 2, v1
	s_mov_b64 s[12:13], 0
	s_branch .LBB0_617

; __device__ __forceinline__ int lane_id_v() { int l; asm volatile("v_mbcnt_lo_u32_b32 %0, -1, 0\n\tv_mbcnt_hi_u32_b32 %0, -1, %0" : "=v"(l)); return l; }
; DI void pool_phase(ArgsP a, int l, const float* XA, bf16_t* Dm, int gt  , int NT  , int lo, int hi  , bool do_sample) {
;     constexpr int NRUN = MP / 8;
;     for (int item = lo + gt; item < hi; item += NT) {
;         const int c4l = item & 31, gr = item >> 5, g = gr / NRUN, run = gr - g * NRUN; const int c4 = g * 128 + c4l * 4, row0 = run * 8;
;         if (g == 0) pool_run<2>(XA, Dm, a->out, l, row0, c4); else if (g == 1) pool_run<4>(XA, Dm, a->out, l, row0, c4);
;         else if (g == 2) pool_run<8>(XA, Dm, a->out, l, row0, c4); else pool_run<16>(XA, Dm, a->out, l, row0, c4);
;     }
; __global__ void __launch_bounds__(512, 2) mega(Args a_unused) {
;     ...
;                   constexpr int NI = 4 * (MP / 8) * 32; const float* XAp = (const float*)(ws + WS_XA); bf16_t* Dp = (bf16_t*)(ws + WS_DYY); const int t_ = wave_s * 64 + lane_id_v();
;                   if (G > 132) { constexpr int SPLIT = (NI / 6 * 5) & ~63;
;                       if (c >= 132) pool_phase(a, l, XAp, Dp, (c - 132) * 512 + t_, (G - 132) * 512, 0, SPLIT, true);
;                       else pool_phase(a, l, XAp, Dp, c * 512 + t_, 132 * 512, SPLIT, NI, false); }
;                   else pool_phase(a, l, XAp, Dp, c * 512 + t_, G * 512, 0, NI, true); } }
.LBB0_742:
	s_andn2_b64 vcc, exec, s[4:5]
	s_cbranch_vccnz .LBB0_878
	s_add_i32 s28, s28, 0xfffef800
	v_add_u32_e32 v114, s28, v114
	s_lshl_b32 s28, s51, 9
	s_mov_b32 s4, 0x40000
	s_add_i32 s28, s28, 0xfffef800
	v_cmp_gt_i32_e32 vcc, s4, v114
	s_and_saveexec_b64 s[4:5], vcc
	s_cbranch_execz .LBB0_870
	s_add_u32 s10, s24, 0x4600000
	s_addc_u32 s11, s25, 0
	s_lshl_b32 s29, s51, 11
	v_lshlrev_b32_e32 v96, 2, v114
	s_add_i32 s29, s29, 0xfffbe000
	s_mov_b64 s[12:13], 0
	v_mov_b32_e32 v115, v114
	s_branch .LBB0_746
.LBB0_745:
	s_or_b64 exec, exec, s[8:9]
	v_add_u32_e32 v115, s28, v115
	s_mov_b32 s6, 0x3ffff
	v_cmp_lt_i32_e32 vcc, s6, v115
	s_or_b64 s[12:13], vcc, s[12:13]
	v_add_u32_e32 v96, s29, v96
	s_andn2_b64 exec, exec, s[12:13]
	s_cbranch_execz .LBB0_870
